# stack: ret ctx units moved to idle WGs of next phase; weight conversion rewritten (balanced flat item list) and run in idle tail of FFN-up phases; widened transposed V stores; in-proj plain tiles stor
# speedup vs baseline: 1.0152x; 1.0105x over previous
.LBB0_88:
	v_readlane_b32 s0, v251, 36
	s_nop 1
	v_lshl_add_u32 v0, s0, 6, v64
	s_mov_b32 s0, s91
	s_cmp_lt_i32 s0, 0
	s_cbranch_scc1 .LBB0_156
	v_mbcnt_lo_u32_b32 v220, -1, 0
	v_mbcnt_hi_u32_b32 v220, -1, v220
	s_load_dword s1, s[64:65], 0x0
	s_add_u32 s2, s62, 0x1bee0000
	s_addc_u32 s3, s63, 0
	v_writelane_b32 v251, s2, 41
	v_writelane_b32 v251, s3, 42
	v_writelane_b32 v252, s56, 26
	v_writelane_b32 v252, s57, 27
	v_readlane_b32 s4, v251, 36
	s_lshl_b32 s0, s91, 3
	s_nop 0
	s_add_i32 s0, s0, s4
	s_mul_i32 s15, s4, 0x2100
	s_movk_i32 s14, 0x3800
	s_mov_b32 s12, 0
	s_waitcnt lgkmcnt(0)
	s_lshl_b32 s1, s1, 3

.Lcvth_job5:
	s_sub_i32 s10, s0, 5504
	v_readlane_b32 s4, v251, 18
	v_readlane_b32 s5, v251, 19
	s_mul_i32 s3, s12, 0x2000000
	s_mov_b32 s8, 32768
	s_mov_b32 s13, 8192
	s_mov_b32 s9, 2048
	s_mov_b32 s2, 5
	s_mov_b32 s11, 22544384
	s_lshr_b32 vcc_lo, s10, 6
	s_and_b32 s10, s10, 63
	s_branch .Lcvth_common

.Lcvth_job7:
	s_sub_i32 s10, s0, 7552
	v_readlane_b32 s4, v251, 18
	v_readlane_b32 s5, v251, 19
	s_mul_i32 s3, s12, 0x2000000
	s_mov_b32 s8, 32768
	s_mov_b32 s13, 24576
	s_mov_b32 s9, 2048
	s_mov_b32 s2, 5
	s_mov_b32 s11, 30932992
	s_lshr_b32 vcc_lo, s10, 6
	s_and_b32 s10, s10, 63
	s_branch .Lcvth_common

.Lcvth_common:
	s_add_u32 s4, s4, s3
	s_addc_u32 s5, s5, 0
	s_lshl_b32 s3, vcc_lo, 6
	s_mul_i32 vcc_hi, s3, s8
	s_add_u32 s4, s4, vcc_hi
	s_addc_u32 s5, s5, 0
	s_lshl_b32 s10, s10, 5
	s_lshl_b32 vcc_hi, s10, 2
	s_add_i32 s13, s13, vcc_hi
	s_add_u32 s4, s4, s13
	s_addc_u32 s5, s5, 0
	v_readlane_b32 s6, v251, 41
	v_readlane_b32 s7, v251, 42
	s_and_b32 s13, s12, 1
	s_mul_i32 s13, s13, 0x3800000
	s_add_i32 s11, s11, s13
	s_lshl_b32 s13, s3, 1
	s_add_i32 s11, s11, s13
	s_add_u32 s6, s6, s11
	s_addc_u32 s7, s7, 0
	s_cmp_eq_u32 s2, 1
	s_cbranch_scc1 .Lcvth_u1
	s_cmp_eq_u32 s2, 2
	s_cbranch_scc1 .Lcvth_u2
	s_cmp_eq_u32 s2, 4
	s_cbranch_scc1 .Lcvth_u4
	s_cmp_eq_u32 s2, 5
	s_cbranch_scc1 .Lcvth_u5
	s_mov_b32 s11, s10
	s_branch .Lcvth_ud

.Lcvth_u5:
	s_and_b32 s11, s10, 0xffffff00
	s_bfe_u32 s3, s10, 0x10005
	s_lshl_b32 s3, s3, 7
	s_add_i32 s11, s11, s3
	s_bfe_u32 s3, s10, 0x20006
	s_lshl_b32 s3, s3, 5
	s_add_i32 s11, s11, s3
	s_branch .Lcvth_ud

.Lcvth_done2:
.LBB0_156:
	s_movk_i32 s32, 0x207
	s_add_u32 s0, s62, 0x22f28000
	s_addc_u32 s1, s63, 0
	v_writelane_b32 v251, s0, 37
	s_waitcnt vmcnt(11)
	v_mbcnt_lo_u32_b32 v0, -1, 0
	s_mov_b32 s89, 1
	v_writelane_b32 v251, s1, 38
	s_add_u32 s0, s62, 0x22f30000
	s_addc_u32 s1, s63, 0
	v_writelane_b32 v251, s0, 39
	s_waitcnt lgkmcnt(0)
	s_movk_i32 s33, 0x3000
	v_mov_b32_e32 v33, 0
	v_writelane_b32 v251, s1, 40
	s_add_u32 s0, s62, 0x1bee0000
	v_writelane_b32 v251, s0, 41
	s_addc_u32 s0, s63, 0
	v_writelane_b32 v251, s0, 42
	s_add_u32 s0, s62, 0x22f38200
	s_addc_u32 s1, s63, 0
	s_add_u32 s2, s62, 0x22f38400
	s_addc_u32 s3, s63, 0
	s_add_u32 s4, s62, 0x22f38500
	s_addc_u32 s5, s63, 0
	s_add_u32 s6, s62, 0x22f38600
	v_writelane_b32 v251, s0, 43
	s_addc_u32 s7, s63, 0
	v_mov_b32_e32 v228, 0x1000
	v_writelane_b32 v251, s1, 44
	s_add_u32 s0, s62, 0x22f38700
	s_addc_u32 s1, s63, 0
	v_writelane_b32 v251, s0, 45
	v_mov_b32_e32 v221, 0x2000
	v_mov_b32_e32 v248, 1
	v_writelane_b32 v251, s1, 46
	s_add_u32 s0, s62, 0x22f38800
	s_addc_u32 s1, s63, 0
	v_writelane_b32 v251, s0, 47
	v_mov_b32_e32 v224, 0x358637bd
	v_mbcnt_hi_u32_b32 v220, -1, v0
	v_writelane_b32 v251, s1, 48
	s_add_u32 s0, s62, 0x22f38900
	s_addc_u32 s1, s63, 0
	v_writelane_b32 v251, s0, 49
	v_mov_b32_e32 v225, 0x42800000
	v_not_b32_e32 v226, 63
	v_writelane_b32 v251, s1, 50
	s_add_u32 s0, s62, 0x22f38a00
	s_addc_u32 s1, s63, 0
	v_writelane_b32 v251, s0, 51
	v_mov_b32_e32 v227, 0x410000
	v_mov_b32_e32 v249, 0x160000
	v_writelane_b32 v251, s1, 52
	s_add_u32 s0, s62, 0x22f38b00
	s_addc_u32 s1, s63, 0
	v_writelane_b32 v251, s0, 53
	s_mov_b32 s94, 0x8200
	s_mov_b32 s66, 0xc2fc0000
	v_writelane_b32 v251, s1, 54
	s_add_u32 s0, s62, 0x22f38c00
	s_addc_u32 s1, s63, 0
	v_writelane_b32 v251, s0, 55
	s_movk_i32 s67, 0xffc0
	s_movk_i32 s88, 0x1000
	v_writelane_b32 v251, s1, 56
	s_add_u32 s0, s62, 0x22f38d00
	s_addc_u32 s1, s63, 0
	v_writelane_b32 v251, s0, 57
	s_mov_b32 s78, 0
	s_mov_b32 s97, 0
	v_writelane_b32 v251, s1, 58
	s_add_u32 s0, s62, 0x22f38e00
	s_addc_u32 s1, s63, 0
	v_writelane_b32 v251, s0, 59
	s_mov_b64 s[34:35], 0x100000
	s_mov_b64 s[68:69], 0x100800
	v_writelane_b32 v251, s1, 60
	s_add_u32 s0, s62, 0x22f38f00
	s_addc_u32 s1, s63, 0
	v_writelane_b32 v251, s0, 61
	s_mov_b64 s[84:85], 0x80
	s_nop 0
	v_writelane_b32 v251, s1, 62
	s_add_u32 s0, s62, 0x22f39000
	s_addc_u32 s1, s63, 0
	v_writelane_b32 v251, s0, 63
	s_nop 1
	v_writelane_b32 v252, s1, 0
	s_add_u32 s0, s62, 0x22f39100
	s_addc_u32 s1, s63, 0
	v_writelane_b32 v252, s0, 1
	s_nop 1
	v_writelane_b32 v252, s1, 2
	s_add_u32 s0, s62, 0x22f39200
	s_addc_u32 s1, s63, 0
	v_writelane_b32 v252, s0, 3
	s_nop 1
	v_writelane_b32 v252, s1, 4
	s_add_u32 s0, s62, 0x22f39300
	s_addc_u32 s1, s63, 0
	v_writelane_b32 v252, s0, 5
	s_nop 1
	v_writelane_b32 v252, s1, 6
	s_add_u32 s0, s62, 0x22f3b400
	s_addc_u32 s1, s63, 0
	s_add_u32 s52, s62, 0x22f3b500
	v_writelane_b32 v252, s0, 7
	s_addc_u32 s53, s63, 0
	s_nop 0
	v_writelane_b32 v252, s1, 8
	s_add_u32 s0, s62, 0x2080000
	s_addc_u32 s1, s63, 0
	v_writelane_b32 v252, s0, 9
	s_nop 1
	v_writelane_b32 v252, s1, 10
	s_add_u32 s0, s62, 0x22f3c000
	s_addc_u32 s1, s63, 0
	s_add_u32 s70, s62, 0x9a60000
	v_writelane_b32 v252, s0, 11
	s_addc_u32 s71, s63, 0
	s_nop 0
	v_writelane_b32 v252, s1, 12
	s_add_u32 s0, s62, 0x8200000
	s_addc_u32 s1, s63, 0
	v_writelane_b32 v252, s0, 13
	s_nop 1
	v_writelane_b32 v252, s1, 14
	s_add_u32 s0, s62, 0x15d60000
	s_addc_u32 s1, s63, 0
	s_add_u32 s92, s62, 0x4100000
	v_writelane_b32 v252, s0, 15
	s_addc_u32 s93, s63, 0
	s_nop 0
	v_writelane_b32 v252, s1, 16
	s_add_u32 s0, s62, 0x19e60000
	s_addc_u32 s1, s63, 0
	v_writelane_b32 v252, s0, 17
	s_nop 1
	v_writelane_b32 v252, s1, 18
	s_add_u32 s0, s62, 0x17de0000
	s_addc_u32 s1, s63, 0
	v_writelane_b32 v252, s0, 19
	s_bitcmp1_b32 s91, 0
	s_nop 0
	v_writelane_b32 v252, s1, 20
	s_cselect_b64 s[0:1], -1, 0
	v_writelane_b32 v252, s0, 21
	s_nop 1
	v_writelane_b32 v252, s1, 22
	s_add_u32 s0, s62, 0x23a3c000
	v_writelane_b32 v252, s0, 23
	s_addc_u32 s0, s63, 0
	v_writelane_b32 v252, s0, 24
	s_add_u32 s0, s62, 0x23abc000
	v_writelane_b32 v252, s0, 25
	v_writelane_b32 v252, s56, 26
	s_addc_u32 s0, s63, 0
	s_add_i32 s80, 0, 0x11000
	v_writelane_b32 v252, s57, 27
	v_writelane_b32 v252, s58, 28
	v_writelane_b32 v252, s59, 29
	v_writelane_b32 v252, s60, 30
	v_writelane_b32 v252, s61, 31
	v_writelane_b32 v252, s62, 32
	v_writelane_b32 v252, s63, 33
	v_writelane_b32 v252, s0, 34
	s_add_i32 s0, 0, 0x23ff0
	v_writelane_b32 v252, s0, 35
	s_add_i32 s0, 0, 0x23ff4
	v_writelane_b32 v252, s0, 36
	s_add_i32 s0, 0, 0x22000
	v_writelane_b32 v252, s0, 37
	v_writelane_b32 v252, s52, 38
	s_mov_b64 s[56:57], s[2:3]
	s_mov_b64 s[58:59], s[4:5]
	v_writelane_b32 v252, s53, 39
	v_writelane_b32 v252, s56, 40
	s_mov_b64 s[60:61], s[6:7]
	s_add_i32 s81, 0, 0x19800
	v_writelane_b32 v252, s57, 41
	v_writelane_b32 v252, s58, 42
	s_nop 1
	v_writelane_b32 v252, s59, 43
	v_writelane_b32 v252, s60, 44
	s_nop 1
	v_writelane_b32 v252, s61, 45
	v_writelane_b32 v252, s91, 46
	v_writelane_b32 v252, s54, 47
	s_nop 1
	v_writelane_b32 v252, s55, 48
	v_writelane_b32 v252, s64, 49
	s_nop 1
	v_writelane_b32 v252, s65, 50

.LBB0_403:
	s_add_u32 s14, s4, 0x100
	s_addc_u32 s15, s5, 0
	s_add_i32 s38, 0, 0x10000
	v_add_u32_e32 v12, s38, v193
	ds_read_b128 v[0:3], v12
	ds_read_b128 v[4:7], v12 offset:1024
	ds_read_b128 v[8:11], v12 offset:2048
	ds_read_b128 v[12:15], v12 offset:3072
	s_cmp_eq_u32 s37, 12
	s_cselect_b32 s19, s9, s15
	s_cselect_b32 s18, s8, s14
	s_cselect_b32 s17, s11, s36
	s_cselect_b32 s16, s10, s7
	v_lshl_add_u64 v[190:191], s[4:5], 0, v[186:187]
	s_add_i32 m0, s23, 0xc000
	ds_read_b128 v[16:19], v206
	ds_read_b128 v[20:23], v206 offset:1024
	ds_read_b128 v[24:27], v206 offset:2048
	ds_read_b128 v[28:31], v206 offset:3072
	ds_read_b128 v[162:165], v206 offset:4096
	ds_read_b128 v[166:169], v206 offset:5120
	ds_read_b128 v[170:173], v206 offset:6144
	ds_read_b128 v[174:177], v206 offset:7168
	global_load_lds_dwordx4 v[190:191], off
	v_lshl_add_u64 v[190:191], s[4:5], 0, v[188:189]
	s_add_i32 m0, s23, 0xe000
	s_nop 0
	global_load_lds_dwordx4 v[190:191], off
	s_waitcnt lgkmcnt(8)
	s_barrier
	s_waitcnt lgkmcnt(0)
	s_setprio 1
	s_waitcnt lgkmcnt(0)
	v_mfma_f32_16x16x32_f16 v[158:161], v[0:3], v[16:19], v[158:161]
	v_mfma_f32_16x16x32_f16 v[142:145], v[8:11], v[16:19], v[142:145]
	v_mfma_f32_16x16x32_f16 v[150:153], v[0:3], v[24:27], v[150:153]
	v_mfma_f32_16x16x32_f16 v[134:137], v[8:11], v[24:27], v[134:137]
	v_mfma_f32_16x16x32_f16 v[154:157], v[0:3], v[162:165], v[154:157]
	v_mfma_f32_16x16x32_f16 v[138:141], v[8:11], v[162:165], v[138:141]
	v_mfma_f32_16x16x32_f16 v[146:149], v[0:3], v[170:173], v[146:149]
	v_mfma_f32_16x16x32_f16 v[130:133], v[8:11], v[170:173], v[130:133]
	v_mfma_f32_16x16x32_f16 v[158:161], v[4:7], v[20:23], v[158:161]
	v_mfma_f32_16x16x32_f16 v[142:145], v[12:15], v[20:23], v[142:145]
	v_mfma_f32_16x16x32_f16 v[150:153], v[4:7], v[28:31], v[150:153]
	v_mfma_f32_16x16x32_f16 v[134:137], v[12:15], v[28:31], v[134:137]
	v_mfma_f32_16x16x32_f16 v[154:157], v[4:7], v[166:169], v[154:157]
	v_mfma_f32_16x16x32_f16 v[138:141], v[12:15], v[166:169], v[138:141]
	v_mfma_f32_16x16x32_f16 v[146:149], v[4:7], v[174:177], v[146:149]
	v_mfma_f32_16x16x32_f16 v[130:133], v[12:15], v[174:177], v[130:133]
	s_setprio 0
	s_barrier
	s_add_i32 s39, 0, 0x14000
	s_add_i32 s4, s38, s22
	v_add_u32_e32 v32, s39, v193
	v_lshl_add_u64 v[190:191], s[16:17], 0, v[178:179]
	s_mov_b32 m0, s4
	ds_read_b128 v[208:211], v32
	ds_read_b128 v[212:215], v32 offset:1024
	ds_read_b128 v[216:219], v32 offset:2048
	ds_read_b128 v[230:233], v32 offset:3072
	global_load_lds_dwordx4 v[190:191], off
	v_lshl_add_u64 v[238:239], s[16:17], 0, v[180:181]
	s_add_i32 m0, s4, 0x2000
	s_nop 0
	global_load_lds_dwordx4 v[238:239], off
	s_barrier
	s_waitcnt lgkmcnt(0)
	s_setprio 1
	s_waitcnt lgkmcnt(0)
	v_mfma_f32_16x16x32_f16 v[94:97], v[208:211], v[16:19], v[94:97]
	v_mfma_f32_16x16x32_f16 v[16:19], v[216:219], v[16:19], v[78:81]
	v_mfma_f32_16x16x32_f16 v[94:97], v[212:215], v[20:23], v[94:97]
	v_mfma_f32_16x16x32_f16 v[16:19], v[230:233], v[20:23], v[16:19]
	v_mfma_f32_16x16x32_f16 v[20:23], v[208:211], v[24:27], v[86:89]
	v_mfma_f32_16x16x32_f16 v[24:27], v[216:219], v[24:27], v[70:73]
	v_mfma_f32_16x16x32_f16 v[70:73], v[216:219], v[162:165], v[74:77]
	v_mfma_f32_16x16x32_f16 v[74:77], v[230:233], v[166:169], v[70:73]
	v_mfma_f32_16x16x32_f16 v[70:73], v[208:211], v[170:173], v[82:85]
	v_mfma_f32_16x16x32_f16 v[66:69], v[216:219], v[170:173], v[66:69]
	v_mfma_f32_16x16x32_f16 v[20:23], v[212:215], v[28:31], v[20:23]
	v_mfma_f32_16x16x32_f16 v[24:27], v[230:233], v[28:31], v[24:27]
	v_mfma_f32_16x16x32_f16 v[28:31], v[208:211], v[162:165], v[90:93]
	v_mfma_f32_16x16x32_f16 v[82:85], v[212:215], v[174:177], v[70:73]
	v_mfma_f32_16x16x32_f16 v[66:69], v[230:233], v[174:177], v[66:69]
	v_mfma_f32_16x16x32_f16 v[28:31], v[212:215], v[166:169], v[28:31]
	s_setprio 0
	s_mov_b32 m0, s23
	v_lshl_add_u64 v[240:241], s[18:19], 0, v[178:179]
	s_barrier
	ds_read_b128 v[70:73], v206 offset:16384
	ds_read_b128 v[78:81], v206 offset:17408
	ds_read_b128 v[86:89], v206 offset:18432
	ds_read_b128 v[90:93], v206 offset:19456
	ds_read_b128 v[162:165], v206 offset:20480
	ds_read_b128 v[166:169], v206 offset:21504
	ds_read_b128 v[170:173], v206 offset:22528
	ds_read_b128 v[174:177], v206 offset:23552
	global_load_lds_dwordx4 v[240:241], off
	v_lshl_add_u64 v[242:243], s[18:19], 0, v[180:181]
	s_mov_b32 m0, s24
	s_nop 0
	global_load_lds_dwordx4 v[242:243], off
	s_barrier
	s_waitcnt lgkmcnt(0)
	s_setprio 1
	s_waitcnt lgkmcnt(0)
	v_mfma_f32_16x16x32_f16 v[126:129], v[0:3], v[70:73], v[126:129]
	v_mfma_f32_16x16x32_f16 v[110:113], v[8:11], v[70:73], v[110:113]
	v_mfma_f32_16x16x32_f16 v[118:121], v[0:3], v[86:89], v[118:121]
	v_mfma_f32_16x16x32_f16 v[102:105], v[8:11], v[86:89], v[102:105]
	v_mfma_f32_16x16x32_f16 v[122:125], v[0:3], v[162:165], v[122:125]
	v_mfma_f32_16x16x32_f16 v[106:109], v[8:11], v[162:165], v[106:109]
	v_mfma_f32_16x16x32_f16 v[0:3], v[0:3], v[170:173], v[114:117]
	v_mfma_f32_16x16x32_f16 v[126:129], v[4:7], v[78:81], v[126:129]
	v_mfma_f32_16x16x32_f16 v[110:113], v[12:15], v[78:81], v[110:113]
	v_mfma_f32_16x16x32_f16 v[118:121], v[4:7], v[90:93], v[118:121]
	v_mfma_f32_16x16x32_f16 v[102:105], v[12:15], v[90:93], v[102:105]
	v_mfma_f32_16x16x32_f16 v[122:125], v[4:7], v[166:169], v[122:125]
	v_mfma_f32_16x16x32_f16 v[106:109], v[12:15], v[166:169], v[106:109]
	v_mfma_f32_16x16x32_f16 v[0:3], v[4:7], v[174:177], v[0:3]
	v_mfma_f32_16x16x32_f16 v[4:7], v[8:11], v[170:173], v[98:101]
	v_mfma_f32_16x16x32_f16 v[4:7], v[12:15], v[174:177], v[4:7]
	s_setprio 0
	s_barrier
	s_add_u32 s4, s16, 0x40000
	s_addc_u32 s5, s17, 0
	s_add_i32 s38, s39, s22
	v_lshl_add_u64 v[8:9], s[4:5], 0, v[178:179]
	s_mov_b32 m0, s38
	s_nop 0
	global_load_lds_dwordx4 v[8:9], off
	v_lshl_add_u64 v[8:9], s[4:5], 0, v[180:181]
	s_add_i32 m0, s38, 0x2000
	s_nop 0
	global_load_lds_dwordx4 v[8:9], off
	s_waitcnt vmcnt(6)
	s_barrier
	s_setprio 1
	v_mfma_f32_16x16x32_f16 v[12:15], v[216:219], v[70:73], v[46:49]
	v_mfma_f32_16x16x32_f16 v[46:49], v[208:211], v[86:89], v[54:57]
	v_mfma_f32_16x16x32_f16 v[54:57], v[212:215], v[90:93], v[46:49]
	v_mfma_f32_16x16x32_f16 v[46:49], v[208:211], v[162:165], v[58:61]
	v_mfma_f32_16x16x32_f16 v[38:41], v[216:219], v[86:89], v[38:41]
	v_mfma_f32_16x16x32_f16 v[58:61], v[212:215], v[166:169], v[46:49]
	v_mfma_f32_16x16x32_f16 v[42:45], v[216:219], v[162:165], v[42:45]
	v_mfma_f32_16x16x32_f16 v[46:49], v[208:211], v[170:173], v[50:53]
	v_mfma_f32_16x16x32_f16 v[34:37], v[216:219], v[170:173], v[34:37]
	v_mfma_f32_16x16x32_f16 v[8:11], v[208:211], v[70:73], v[62:65]
	v_mfma_f32_16x16x32_f16 v[38:41], v[230:233], v[90:93], v[38:41]
	v_mfma_f32_16x16x32_f16 v[42:45], v[230:233], v[166:169], v[42:45]
	v_mfma_f32_16x16x32_f16 v[50:53], v[212:215], v[174:177], v[46:49]
	v_mfma_f32_16x16x32_f16 v[34:37], v[230:233], v[174:177], v[34:37]
	v_mfma_f32_16x16x32_f16 v[8:11], v[212:215], v[78:81], v[8:11]
	v_mfma_f32_16x16x32_f16 v[12:15], v[230:233], v[78:81], v[12:15]
	s_setprio 0
	s_add_i32 s38, 0, 0x18000
	v_add_u32_e32 v32, s38, v193
	s_barrier
	ds_read_b128 v[46:49], v32
	ds_read_b128 v[62:65], v32 offset:1024
	ds_read_b128 v[98:101], v32 offset:2048
	ds_read_b128 v[162:165], v32 offset:3072
	s_add_u32 s4, s18, 0x40000
	s_addc_u32 s5, s19, 0
	s_mov_b32 m0, s25
	v_lshl_add_u64 v[86:87], s[4:5], 0, v[178:179]
	ds_read_b128 v[70:73], v206 offset:32768
	ds_read_b128 v[78:81], v206 offset:33792
	ds_read_b128 v[90:93], v206 offset:34816
	ds_read_b128 v[114:117], v206 offset:35840
	ds_read_b128 v[166:169], v206 offset:36864
	ds_read_b128 v[170:173], v206 offset:37888
	ds_read_b128 v[174:177], v206 offset:38912
	ds_read_b128 v[208:211], v206 offset:39936
	global_load_lds_dwordx4 v[86:87], off
	v_lshl_add_u64 v[86:87], s[4:5], 0, v[180:181]
	s_mov_b32 m0, s26
	s_nop 0
	global_load_lds_dwordx4 v[86:87], off
	s_waitcnt lgkmcnt(8)
	s_barrier
	s_waitcnt lgkmcnt(0)
	s_setprio 1
	s_waitcnt lgkmcnt(0)
	v_mfma_f32_16x16x32_f16 v[86:89], v[46:49], v[70:73], v[158:161]
	v_mfma_f32_16x16x32_f16 v[158:161], v[62:65], v[78:81], v[86:89]
	v_mfma_f32_16x16x32_f16 v[86:89], v[98:101], v[70:73], v[142:145]
	v_mfma_f32_16x16x32_f16 v[142:145], v[162:165], v[78:81], v[86:89]
	v_mfma_f32_16x16x32_f16 v[86:89], v[46:49], v[90:93], v[150:153]
	v_mfma_f32_16x16x32_f16 v[150:153], v[62:65], v[114:117], v[86:89]
	v_mfma_f32_16x16x32_f16 v[86:89], v[98:101], v[90:93], v[134:137]
	v_mfma_f32_16x16x32_f16 v[134:137], v[162:165], v[114:117], v[86:89]
	v_mfma_f32_16x16x32_f16 v[86:89], v[46:49], v[166:169], v[154:157]
	v_mfma_f32_16x16x32_f16 v[154:157], v[62:65], v[170:173], v[86:89]
	v_mfma_f32_16x16x32_f16 v[86:89], v[98:101], v[166:169], v[138:141]
	v_mfma_f32_16x16x32_f16 v[138:141], v[162:165], v[170:173], v[86:89]
	v_mfma_f32_16x16x32_f16 v[86:89], v[46:49], v[174:177], v[146:149]
	v_mfma_f32_16x16x32_f16 v[146:149], v[62:65], v[208:211], v[86:89]
	v_mfma_f32_16x16x32_f16 v[86:89], v[98:101], v[174:177], v[130:133]
	v_mfma_f32_16x16x32_f16 v[130:133], v[162:165], v[208:211], v[86:89]
	s_setprio 0
	s_barrier
	s_add_i32 s18, 0, 0x1c000
	s_add_i32 s4, s38, s22
	v_add_u32_e32 v32, s18, v193
	s_nop 1
	v_lshl_add_u64 v[86:87], v[190:191], 0, s[84:85]
	s_mov_b32 m0, s4
	ds_read_b128 v[212:215], v32
	ds_read_b128 v[216:219], v32 offset:1024
	ds_read_b128 v[230:233], v32 offset:2048
	ds_read_b128 v[234:237], v32 offset:3072
	global_load_lds_dwordx4 v[86:87], off
	v_lshl_add_u64 v[86:87], v[238:239], 0, s[84:85]
	s_add_i32 m0, s4, 0x2000
	s_nop 0
	global_load_lds_dwordx4 v[86:87], off
	s_barrier
	s_waitcnt lgkmcnt(0)
	s_setprio 1
	s_waitcnt lgkmcnt(0)
	v_mfma_f32_16x16x32_f16 v[86:89], v[212:215], v[70:73], v[94:97]
	v_mfma_f32_16x16x32_f16 v[16:19], v[230:233], v[70:73], v[16:19]
	v_mfma_f32_16x16x32_f16 v[94:97], v[216:219], v[78:81], v[86:89]
	v_mfma_f32_16x16x32_f16 v[78:81], v[234:237], v[78:81], v[16:19]
	v_mfma_f32_16x16x32_f16 v[16:19], v[212:215], v[90:93], v[20:23]
	v_mfma_f32_16x16x32_f16 v[86:89], v[216:219], v[114:117], v[16:19]
	v_mfma_f32_16x16x32_f16 v[16:19], v[230:233], v[90:93], v[24:27]
	v_mfma_f32_16x16x32_f16 v[70:73], v[234:237], v[114:117], v[16:19]
	v_mfma_f32_16x16x32_f16 v[16:19], v[212:215], v[166:169], v[28:31]
	v_mfma_f32_16x16x32_f16 v[90:93], v[216:219], v[170:173], v[16:19]
	v_mfma_f32_16x16x32_f16 v[16:19], v[230:233], v[166:169], v[74:77]
	v_mfma_f32_16x16x32_f16 v[74:77], v[234:237], v[170:173], v[16:19]
	v_mfma_f32_16x16x32_f16 v[16:19], v[212:215], v[174:177], v[82:85]
	v_mfma_f32_16x16x32_f16 v[82:85], v[216:219], v[208:211], v[16:19]
	v_mfma_f32_16x16x32_f16 v[16:19], v[230:233], v[174:177], v[66:69]
	v_mfma_f32_16x16x32_f16 v[66:69], v[234:237], v[208:211], v[16:19]
	s_setprio 0
	s_mov_b32 m0, s28
	v_lshl_add_u64 v[114:115], v[240:241], 0, s[84:85]
	s_barrier
	s_nop 2
	ds_read_b128 v[16:19], v206 offset:49152
	ds_read_b128 v[20:23], v206 offset:50176
	ds_read_b128 v[24:27], v206 offset:51200
	ds_read_b128 v[28:31], v206 offset:52224
	ds_read_b128 v[166:169], v206 offset:53248
	ds_read_b128 v[170:173], v206 offset:54272
	ds_read_b128 v[174:177], v206 offset:55296
	ds_read_b128 v[208:211], v206 offset:56320
	global_load_lds_dwordx4 v[114:115], off
	v_lshl_add_u64 v[114:115], v[242:243], 0, s[84:85]
	s_mov_b32 m0, s29
	s_nop 0
	global_load_lds_dwordx4 v[114:115], off
	s_barrier
	s_waitcnt lgkmcnt(0)
	s_setprio 1
	s_waitcnt lgkmcnt(0)
	v_mfma_f32_16x16x32_f16 v[114:117], v[46:49], v[16:19], v[126:129]
	v_mfma_f32_16x16x32_f16 v[126:129], v[62:65], v[20:23], v[114:117]
	v_mfma_f32_16x16x32_f16 v[114:117], v[46:49], v[24:27], v[118:121]
	v_mfma_f32_16x16x32_f16 v[118:121], v[62:65], v[28:31], v[114:117]
	v_mfma_f32_16x16x32_f16 v[114:117], v[46:49], v[166:169], v[122:125]
	v_mfma_f32_16x16x32_f16 v[0:3], v[46:49], v[174:177], v[0:3]
	v_mfma_f32_16x16x32_f16 v[110:113], v[98:101], v[16:19], v[110:113]
	v_mfma_f32_16x16x32_f16 v[102:105], v[98:101], v[24:27], v[102:105]
	v_mfma_f32_16x16x32_f16 v[122:125], v[62:65], v[170:173], v[114:117]
	v_mfma_f32_16x16x32_f16 v[106:109], v[98:101], v[166:169], v[106:109]
	v_mfma_f32_16x16x32_f16 v[114:117], v[62:65], v[208:211], v[0:3]
	v_mfma_f32_16x16x32_f16 v[0:3], v[98:101], v[174:177], v[4:7]
	v_mfma_f32_16x16x32_f16 v[110:113], v[162:165], v[20:23], v[110:113]
	v_mfma_f32_16x16x32_f16 v[102:105], v[162:165], v[28:31], v[102:105]
	v_mfma_f32_16x16x32_f16 v[106:109], v[162:165], v[170:173], v[106:109]
	v_mfma_f32_16x16x32_f16 v[98:101], v[162:165], v[208:211], v[0:3]
	s_setprio 0
	s_barrier
	s_add_u32 s4, s16, 0x40080
	s_addc_u32 s5, s17, 0
	s_add_i32 s16, s18, s22
	v_lshl_add_u64 v[0:1], s[4:5], 0, v[178:179]
	s_mov_b32 m0, s16
	s_nop 0
	global_load_lds_dwordx4 v[0:1], off
	v_lshl_add_u64 v[0:1], s[4:5], 0, v[180:181]
	s_add_i32 m0, s16, 0x2000
	s_nop 0
	global_load_lds_dwordx4 v[0:1], off
	s_waitcnt vmcnt(6)
	s_barrier
	s_setprio 1
	v_mfma_f32_16x16x32_f16 v[0:3], v[212:215], v[16:19], v[8:11]
	v_mfma_f32_16x16x32_f16 v[62:65], v[216:219], v[20:23], v[0:3]
	v_mfma_f32_16x16x32_f16 v[0:3], v[230:233], v[16:19], v[12:15]
	v_mfma_f32_16x16x32_f16 v[46:49], v[234:237], v[20:23], v[0:3]
	v_mfma_f32_16x16x32_f16 v[0:3], v[212:215], v[24:27], v[54:57]
	v_mfma_f32_16x16x32_f16 v[54:57], v[216:219], v[28:31], v[0:3]
	v_mfma_f32_16x16x32_f16 v[0:3], v[230:233], v[24:27], v[38:41]
	v_mfma_f32_16x16x32_f16 v[38:41], v[234:237], v[28:31], v[0:3]
	v_mfma_f32_16x16x32_f16 v[0:3], v[212:215], v[166:169], v[58:61]
	v_mfma_f32_16x16x32_f16 v[58:61], v[216:219], v[170:173], v[0:3]
	v_mfma_f32_16x16x32_f16 v[0:3], v[230:233], v[166:169], v[42:45]
	v_mfma_f32_16x16x32_f16 v[42:45], v[234:237], v[170:173], v[0:3]
	v_mfma_f32_16x16x32_f16 v[0:3], v[212:215], v[174:177], v[50:53]
	v_mfma_f32_16x16x32_f16 v[50:53], v[216:219], v[208:211], v[0:3]
	v_mfma_f32_16x16x32_f16 v[0:3], v[230:233], v[174:177], v[34:37]
	v_mfma_f32_16x16x32_f16 v[34:37], v[234:237], v[208:211], v[0:3]
	s_setprio 0
	s_add_i32 s37, s37, 2
	s_add_u32 s7, s7, 0x100
	s_addc_u32 s36, s36, 0
	s_cmp_gt_u32 s37, 13
	s_mov_b64 s[4:5], s[14:15]
	s_barrier
	s_cbranch_scc0 .LBB0_403
	s_lshl_b32 s7, s34, 8
	s_cmp_lt_i32 s35, 28
	s_mov_b64 s[4:5], -1
	s_cbranch_scc0 .LBB0_431
	s_add_i32 s16, s7, s27
	v_or_b32_e32 v207, s16, v192
	s_cmp_gt_i32 s35, 3
	s_cbranch_scc0 .LBB0_411
	s_add_i32 s4, s35, -12
	s_cmp_gt_u32 s4, 7
	s_mov_b64 s[4:5], -1
	s_cbranch_scc0 .LBB0_408
	s_lshl_b32 s4, s35, 8
	s_add_i32 s5, s4, 0xfffffc00
	s_cmp_lt_u32 s35, 12
	s_cselect_b32 s4, s4, s5
	v_and_b32_e32 v10, 7, v220
	v_and_b32_e32 v11, 8, v220
	v_cmp_ne_u32_e32 vcc, 0, v11
	v_and_b32_e32 v12, 0x60, v194
	v_lshlrev_b32_e32 v12, 1, v12
	v_lshl_or_b32 v12, v11, 2, v12
	v_and_b32_e32 v13, 0x18, v194
	v_or_b32_e32 v12, v12, v13
	v_or_b32_e32 v32, s4, v12
	v_or_b32_e32 v14, s16, v10
	v_mov_b64_e32 v[4:5], s[70:71]
	v_mad_i64_i32 v[0:1], s[4:5], v14, s33, v[4:5]
	v_lshlrev_b64 v[6:7], 1, v[32:33]
	v_lshl_add_u64 v[16:17], v[0:1], 0, v[6:7]
	v_mov_b32_e32 v32, 0x30000
	v_lshl_add_u64 v[18:19], v[16:17], 0, v[32:33]
	v_lshl_add_u64 v[20:21], v[18:19], 0, v[32:33]
	v_lshl_add_u64 v[22:23], v[20:21], 0, v[32:33]
	v_mov_b32_e32 v8, 0x180000
	v_mov_b32_e32 v9, 0
	v_lshl_add_u64 v[24:25], v[16:17], 0, v[8:9]
	v_lshl_add_u64 v[26:27], v[24:25], 0, v[32:33]
	v_lshl_add_u64 v[28:29], v[26:27], 0, v[32:33]
	v_lshl_add_u64 v[30:31], v[28:29], 0, v[32:33]
	v_mov_b32_e32 v8, 0x18000
	v_cvt_pk_f16_f32 v158, v158, v159
	v_cvt_pk_f16_f32 v159, v160, v161
	v_cvt_pk_f16_f32 v160, v142, v143
	v_cvt_pk_f16_f32 v161, v144, v145
	v_cvt_pk_f16_f32 v94, v94, v95
	v_cvt_pk_f16_f32 v95, v96, v97
	v_cvt_pk_f16_f32 v96, v78, v79
	v_cvt_pk_f16_f32 v97, v80, v81
	v_mov_b32_dpp v0, v158 row_ror:8 row_mask:0xf bank_mask:0xf
	v_mov_b32_dpp v1, v159 row_ror:8 row_mask:0xf bank_mask:0xf
	v_mov_b32_dpp v2, v160 row_ror:8 row_mask:0xf bank_mask:0xf
	v_mov_b32_dpp v3, v161 row_ror:8 row_mask:0xf bank_mask:0xf
	v_mov_b32_dpp v4, v94 row_ror:8 row_mask:0xf bank_mask:0xf
	v_mov_b32_dpp v5, v95 row_ror:8 row_mask:0xf bank_mask:0xf
	v_mov_b32_dpp v6, v96 row_ror:8 row_mask:0xf bank_mask:0xf
	v_mov_b32_dpp v7, v97 row_ror:8 row_mask:0xf bank_mask:0xf
	v_cndmask_b32_e32 v158, v158, v4, vcc
	v_cndmask_b32_e32 v159, v159, v5, vcc
	v_cndmask_b32_e32 v160, v160, v6, vcc
	v_cndmask_b32_e32 v161, v161, v7, vcc
	v_cndmask_b32_e32 v94, v0, v94, vcc
	v_cndmask_b32_e32 v95, v1, v95, vcc
	v_cndmask_b32_e32 v96, v2, v96, vcc
	v_cndmask_b32_e32 v97, v3, v97, vcc
	v_lshl_add_u64 v[10:11], v[16:17], 0, v[8:9]
	global_store_dwordx4 v[16:17], v[158:161], off
	global_store_dwordx4 v[10:11], v[94:97], off
	v_cvt_pk_f16_f32 v150, v150, v151
	v_cvt_pk_f16_f32 v151, v152, v153
	v_cvt_pk_f16_f32 v152, v134, v135
	v_cvt_pk_f16_f32 v153, v136, v137
	v_cvt_pk_f16_f32 v86, v86, v87
	v_cvt_pk_f16_f32 v87, v88, v89
	v_cvt_pk_f16_f32 v88, v70, v71
	v_cvt_pk_f16_f32 v89, v72, v73
	v_mov_b32_dpp v0, v150 row_ror:8 row_mask:0xf bank_mask:0xf
	v_mov_b32_dpp v1, v151 row_ror:8 row_mask:0xf bank_mask:0xf
	v_mov_b32_dpp v2, v152 row_ror:8 row_mask:0xf bank_mask:0xf
	v_mov_b32_dpp v3, v153 row_ror:8 row_mask:0xf bank_mask:0xf
	v_mov_b32_dpp v4, v86 row_ror:8 row_mask:0xf bank_mask:0xf
	v_mov_b32_dpp v5, v87 row_ror:8 row_mask:0xf bank_mask:0xf
	v_mov_b32_dpp v6, v88 row_ror:8 row_mask:0xf bank_mask:0xf
	v_mov_b32_dpp v7, v89 row_ror:8 row_mask:0xf bank_mask:0xf
	v_cndmask_b32_e32 v150, v150, v4, vcc
	v_cndmask_b32_e32 v151, v151, v5, vcc
	v_cndmask_b32_e32 v152, v152, v6, vcc
	v_cndmask_b32_e32 v153, v153, v7, vcc
	v_cndmask_b32_e32 v86, v0, v86, vcc
	v_cndmask_b32_e32 v87, v1, v87, vcc
	v_cndmask_b32_e32 v88, v2, v88, vcc
	v_cndmask_b32_e32 v89, v3, v89, vcc
	v_lshl_add_u64 v[10:11], v[18:19], 0, v[8:9]
	global_store_dwordx4 v[18:19], v[150:153], off
	global_store_dwordx4 v[10:11], v[86:89], off
	v_cvt_pk_f16_f32 v154, v154, v155
	v_cvt_pk_f16_f32 v155, v156, v157
	v_cvt_pk_f16_f32 v156, v138, v139
	v_cvt_pk_f16_f32 v157, v140, v141
	v_cvt_pk_f16_f32 v90, v90, v91
	v_cvt_pk_f16_f32 v91, v92, v93
	v_cvt_pk_f16_f32 v92, v74, v75
	v_cvt_pk_f16_f32 v93, v76, v77
	v_mov_b32_dpp v0, v154 row_ror:8 row_mask:0xf bank_mask:0xf
	v_mov_b32_dpp v1, v155 row_ror:8 row_mask:0xf bank_mask:0xf
	v_mov_b32_dpp v2, v156 row_ror:8 row_mask:0xf bank_mask:0xf
	v_mov_b32_dpp v3, v157 row_ror:8 row_mask:0xf bank_mask:0xf
	v_mov_b32_dpp v4, v90 row_ror:8 row_mask:0xf bank_mask:0xf
	v_mov_b32_dpp v5, v91 row_ror:8 row_mask:0xf bank_mask:0xf
	v_mov_b32_dpp v6, v92 row_ror:8 row_mask:0xf bank_mask:0xf
	v_mov_b32_dpp v7, v93 row_ror:8 row_mask:0xf bank_mask:0xf
	v_cndmask_b32_e32 v154, v154, v4, vcc
	v_cndmask_b32_e32 v155, v155, v5, vcc
	v_cndmask_b32_e32 v156, v156, v6, vcc
	v_cndmask_b32_e32 v157, v157, v7, vcc
	v_cndmask_b32_e32 v90, v0, v90, vcc
	v_cndmask_b32_e32 v91, v1, v91, vcc
	v_cndmask_b32_e32 v92, v2, v92, vcc
	v_cndmask_b32_e32 v93, v3, v93, vcc
	v_lshl_add_u64 v[10:11], v[20:21], 0, v[8:9]
	global_store_dwordx4 v[20:21], v[154:157], off
	global_store_dwordx4 v[10:11], v[90:93], off
	v_cvt_pk_f16_f32 v146, v146, v147
	v_cvt_pk_f16_f32 v147, v148, v149
	v_cvt_pk_f16_f32 v148, v130, v131
	v_cvt_pk_f16_f32 v149, v132, v133
	v_cvt_pk_f16_f32 v82, v82, v83
	v_cvt_pk_f16_f32 v83, v84, v85
	v_cvt_pk_f16_f32 v84, v66, v67
	v_cvt_pk_f16_f32 v85, v68, v69
	v_mov_b32_dpp v0, v146 row_ror:8 row_mask:0xf bank_mask:0xf
	v_mov_b32_dpp v1, v147 row_ror:8 row_mask:0xf bank_mask:0xf
	v_mov_b32_dpp v2, v148 row_ror:8 row_mask:0xf bank_mask:0xf
	v_mov_b32_dpp v3, v149 row_ror:8 row_mask:0xf bank_mask:0xf
	v_mov_b32_dpp v4, v82 row_ror:8 row_mask:0xf bank_mask:0xf
	v_mov_b32_dpp v5, v83 row_ror:8 row_mask:0xf bank_mask:0xf
	v_mov_b32_dpp v6, v84 row_ror:8 row_mask:0xf bank_mask:0xf
	v_mov_b32_dpp v7, v85 row_ror:8 row_mask:0xf bank_mask:0xf
	v_cndmask_b32_e32 v146, v146, v4, vcc
	v_cndmask_b32_e32 v147, v147, v5, vcc
	v_cndmask_b32_e32 v148, v148, v6, vcc
	v_cndmask_b32_e32 v149, v149, v7, vcc
	v_cndmask_b32_e32 v82, v0, v82, vcc
	v_cndmask_b32_e32 v83, v1, v83, vcc
	v_cndmask_b32_e32 v84, v2, v84, vcc
	v_cndmask_b32_e32 v85, v3, v85, vcc
	v_lshl_add_u64 v[10:11], v[22:23], 0, v[8:9]
	global_store_dwordx4 v[22:23], v[146:149], off
	global_store_dwordx4 v[10:11], v[82:85], off
	v_cvt_pk_f16_f32 v126, v126, v127
	v_cvt_pk_f16_f32 v127, v128, v129
	v_cvt_pk_f16_f32 v128, v110, v111
	v_cvt_pk_f16_f32 v129, v112, v113
	v_cvt_pk_f16_f32 v62, v62, v63
	v_cvt_pk_f16_f32 v63, v64, v65
	v_cvt_pk_f16_f32 v64, v46, v47
	v_cvt_pk_f16_f32 v65, v48, v49
	v_mov_b32_dpp v0, v126 row_ror:8 row_mask:0xf bank_mask:0xf
	v_mov_b32_dpp v1, v127 row_ror:8 row_mask:0xf bank_mask:0xf
	v_mov_b32_dpp v2, v128 row_ror:8 row_mask:0xf bank_mask:0xf
	v_mov_b32_dpp v3, v129 row_ror:8 row_mask:0xf bank_mask:0xf
	v_mov_b32_dpp v4, v62 row_ror:8 row_mask:0xf bank_mask:0xf
	v_mov_b32_dpp v5, v63 row_ror:8 row_mask:0xf bank_mask:0xf
	v_mov_b32_dpp v6, v64 row_ror:8 row_mask:0xf bank_mask:0xf
	v_mov_b32_dpp v7, v65 row_ror:8 row_mask:0xf bank_mask:0xf
	v_cndmask_b32_e32 v126, v126, v4, vcc
	v_cndmask_b32_e32 v127, v127, v5, vcc
	v_cndmask_b32_e32 v128, v128, v6, vcc
	v_cndmask_b32_e32 v129, v129, v7, vcc
	v_cndmask_b32_e32 v62, v0, v62, vcc
	v_cndmask_b32_e32 v63, v1, v63, vcc
	v_cndmask_b32_e32 v64, v2, v64, vcc
	v_cndmask_b32_e32 v65, v3, v65, vcc
	v_lshl_add_u64 v[10:11], v[24:25], 0, v[8:9]
	global_store_dwordx4 v[24:25], v[126:129], off
	global_store_dwordx4 v[10:11], v[62:65], off
	v_cvt_pk_f16_f32 v118, v118, v119
	v_cvt_pk_f16_f32 v119, v120, v121
	v_cvt_pk_f16_f32 v120, v102, v103
	v_cvt_pk_f16_f32 v121, v104, v105
	v_cvt_pk_f16_f32 v54, v54, v55
	v_cvt_pk_f16_f32 v55, v56, v57
	v_cvt_pk_f16_f32 v56, v38, v39
	v_cvt_pk_f16_f32 v57, v40, v41
	v_mov_b32_dpp v0, v118 row_ror:8 row_mask:0xf bank_mask:0xf
	v_mov_b32_dpp v1, v119 row_ror:8 row_mask:0xf bank_mask:0xf
	v_mov_b32_dpp v2, v120 row_ror:8 row_mask:0xf bank_mask:0xf
	v_mov_b32_dpp v3, v121 row_ror:8 row_mask:0xf bank_mask:0xf
	v_mov_b32_dpp v4, v54 row_ror:8 row_mask:0xf bank_mask:0xf
	v_mov_b32_dpp v5, v55 row_ror:8 row_mask:0xf bank_mask:0xf
	v_mov_b32_dpp v6, v56 row_ror:8 row_mask:0xf bank_mask:0xf
	v_mov_b32_dpp v7, v57 row_ror:8 row_mask:0xf bank_mask:0xf
	v_cndmask_b32_e32 v118, v118, v4, vcc
	v_cndmask_b32_e32 v119, v119, v5, vcc
	v_cndmask_b32_e32 v120, v120, v6, vcc
	v_cndmask_b32_e32 v121, v121, v7, vcc
	v_cndmask_b32_e32 v54, v0, v54, vcc
	v_cndmask_b32_e32 v55, v1, v55, vcc
	v_cndmask_b32_e32 v56, v2, v56, vcc
	v_cndmask_b32_e32 v57, v3, v57, vcc
	v_lshl_add_u64 v[10:11], v[26:27], 0, v[8:9]
	global_store_dwordx4 v[26:27], v[118:121], off
	global_store_dwordx4 v[10:11], v[54:57], off
	v_cvt_pk_f16_f32 v122, v122, v123
	v_cvt_pk_f16_f32 v123, v124, v125
	v_cvt_pk_f16_f32 v124, v106, v107
	v_cvt_pk_f16_f32 v125, v108, v109
	v_cvt_pk_f16_f32 v58, v58, v59
	v_cvt_pk_f16_f32 v59, v60, v61
	v_cvt_pk_f16_f32 v60, v42, v43
	v_cvt_pk_f16_f32 v61, v44, v45
	v_mov_b32_dpp v0, v122 row_ror:8 row_mask:0xf bank_mask:0xf
	v_mov_b32_dpp v1, v123 row_ror:8 row_mask:0xf bank_mask:0xf
	v_mov_b32_dpp v2, v124 row_ror:8 row_mask:0xf bank_mask:0xf
	v_mov_b32_dpp v3, v125 row_ror:8 row_mask:0xf bank_mask:0xf
	v_mov_b32_dpp v4, v58 row_ror:8 row_mask:0xf bank_mask:0xf
	v_mov_b32_dpp v5, v59 row_ror:8 row_mask:0xf bank_mask:0xf
	v_mov_b32_dpp v6, v60 row_ror:8 row_mask:0xf bank_mask:0xf
	v_mov_b32_dpp v7, v61 row_ror:8 row_mask:0xf bank_mask:0xf
	v_cndmask_b32_e32 v122, v122, v4, vcc
	v_cndmask_b32_e32 v123, v123, v5, vcc
	v_cndmask_b32_e32 v124, v124, v6, vcc
	v_cndmask_b32_e32 v125, v125, v7, vcc
	v_cndmask_b32_e32 v58, v0, v58, vcc
	v_cndmask_b32_e32 v59, v1, v59, vcc
	v_cndmask_b32_e32 v60, v2, v60, vcc
	v_cndmask_b32_e32 v61, v3, v61, vcc
	v_lshl_add_u64 v[10:11], v[28:29], 0, v[8:9]
	global_store_dwordx4 v[28:29], v[122:125], off
	global_store_dwordx4 v[10:11], v[58:61], off
	v_cvt_pk_f16_f32 v114, v114, v115
	v_cvt_pk_f16_f32 v115, v116, v117
	v_cvt_pk_f16_f32 v116, v98, v99
	v_cvt_pk_f16_f32 v117, v100, v101
	v_cvt_pk_f16_f32 v50, v50, v51
	v_cvt_pk_f16_f32 v51, v52, v53
	v_cvt_pk_f16_f32 v52, v34, v35
	v_cvt_pk_f16_f32 v53, v36, v37
	v_mov_b32_dpp v0, v114 row_ror:8 row_mask:0xf bank_mask:0xf
	v_mov_b32_dpp v1, v115 row_ror:8 row_mask:0xf bank_mask:0xf
	v_mov_b32_dpp v2, v116 row_ror:8 row_mask:0xf bank_mask:0xf
	v_mov_b32_dpp v3, v117 row_ror:8 row_mask:0xf bank_mask:0xf
	v_mov_b32_dpp v4, v50 row_ror:8 row_mask:0xf bank_mask:0xf
	v_mov_b32_dpp v5, v51 row_ror:8 row_mask:0xf bank_mask:0xf
	v_mov_b32_dpp v6, v52 row_ror:8 row_mask:0xf bank_mask:0xf
	v_mov_b32_dpp v7, v53 row_ror:8 row_mask:0xf bank_mask:0xf
	v_cndmask_b32_e32 v114, v114, v4, vcc
	v_cndmask_b32_e32 v115, v115, v5, vcc
	v_cndmask_b32_e32 v116, v116, v6, vcc
	v_cndmask_b32_e32 v117, v117, v7, vcc
	v_cndmask_b32_e32 v50, v0, v50, vcc
	v_cndmask_b32_e32 v51, v1, v51, vcc
	v_cndmask_b32_e32 v52, v2, v52, vcc
	v_cndmask_b32_e32 v53, v3, v53, vcc
	v_lshl_add_u64 v[10:11], v[30:31], 0, v[8:9]
	global_store_dwordx4 v[30:31], v[114:117], off
	global_store_dwordx4 v[10:11], v[50:53], off
	s_mov_b64 s[4:5], 0

.LBB0_431:
	s_andn2_b64 vcc, exec, s[4:5]
	s_cbranch_vccnz .LBB0_391
	v_or_b32_e32 v0, s7, v199
	s_lshl_b32 s7, s35, 8
	s_cmp_lt_u32 s35, 30
	s_mov_b64 s[4:5], -1
	v_ashrrev_i32_e32 v1, 31, v0
	s_cbranch_scc1 .LBB0_434
	v_readlane_b32 s4, v252, 15
	v_readlane_b32 s5, v252, 16
	v_lshrrev_b32_e32 v2, 4, v220
	v_and_b32_e32 v0, 0xffffffe0, v0
	v_lshl_or_b32 v0, v2, 3, v0
	v_ashrrev_i32_e32 v1, 31, v0
	v_add_u32_e32 v10, s7, v200
	v_lshlrev_b64 v[6:7], 1, v[0:1]
	v_mov_b64_e32 v[2:3], s[4:5]
	v_mad_i64_i32 v[4:5], s[4:5], v10, s94, v[2:3]
	v_lshl_add_u64 v[4:5], v[4:5], 0, v[6:7]
	v_cvt_pk_f16_f32 v158, v158, v159
	v_cvt_pk_f16_f32 v159, v160, v161
	v_cvt_pk_f16_f32 v160, v142, v143
	v_cvt_pk_f16_f32 v161, v144, v145
	v_cvt_pk_f16_f32 v94, v94, v95
	v_cvt_pk_f16_f32 v95, v96, v97
	v_cvt_pk_f16_f32 v96, v78, v79
	v_cvt_pk_f16_f32 v97, v80, v81
	v_permlane32_swap_b32_e32 v158, v160
	v_permlane32_swap_b32_e32 v159, v161
	v_permlane32_swap_b32_e32 v94, v96
	v_permlane32_swap_b32_e32 v95, v97
	v_permlane16_swap_b32_e32 v158, v160
	v_permlane16_swap_b32_e32 v159, v161
	v_permlane16_swap_b32_e32 v94, v96
	v_permlane16_swap_b32_e32 v95, v97
	s_nop 1
	global_store_dwordx4 v[4:5], v[158:161], off
	global_store_dwordx4 v[4:5], v[94:97], off offset:256
	s_nop 1
	v_or_b32_e32 v4, 16, v10
	v_mad_i64_i32 v[4:5], s[4:5], v4, s94, v[2:3]
	v_lshl_add_u64 v[4:5], v[4:5], 0, v[6:7]
	v_cvt_pk_f16_f32 v150, v150, v151
	v_cvt_pk_f16_f32 v151, v152, v153
	v_cvt_pk_f16_f32 v152, v134, v135
	v_cvt_pk_f16_f32 v153, v136, v137
	v_cvt_pk_f16_f32 v86, v86, v87
	v_cvt_pk_f16_f32 v87, v88, v89
	v_cvt_pk_f16_f32 v88, v70, v71
	v_cvt_pk_f16_f32 v89, v72, v73
	v_permlane32_swap_b32_e32 v150, v152
	v_permlane32_swap_b32_e32 v151, v153
	v_permlane32_swap_b32_e32 v86, v88
	v_permlane32_swap_b32_e32 v87, v89
	v_permlane16_swap_b32_e32 v150, v152
	v_permlane16_swap_b32_e32 v151, v153
	v_permlane16_swap_b32_e32 v86, v88
	v_permlane16_swap_b32_e32 v87, v89
	s_nop 1
	global_store_dwordx4 v[4:5], v[150:153], off
	global_store_dwordx4 v[4:5], v[86:89], off offset:256
	s_nop 1
	v_or_b32_e32 v4, 32, v10
	v_mad_i64_i32 v[4:5], s[4:5], v4, s94, v[2:3]
	v_lshl_add_u64 v[4:5], v[4:5], 0, v[6:7]
	v_cvt_pk_f16_f32 v154, v154, v155
	v_cvt_pk_f16_f32 v155, v156, v157
	v_cvt_pk_f16_f32 v156, v138, v139
	v_cvt_pk_f16_f32 v157, v140, v141
	v_cvt_pk_f16_f32 v90, v90, v91
	v_cvt_pk_f16_f32 v91, v92, v93
	v_cvt_pk_f16_f32 v92, v74, v75
	v_cvt_pk_f16_f32 v93, v76, v77
	v_permlane32_swap_b32_e32 v154, v156
	v_permlane32_swap_b32_e32 v155, v157
	v_permlane32_swap_b32_e32 v90, v92
	v_permlane32_swap_b32_e32 v91, v93
	v_permlane16_swap_b32_e32 v154, v156
	v_permlane16_swap_b32_e32 v155, v157
	v_permlane16_swap_b32_e32 v90, v92
	v_permlane16_swap_b32_e32 v91, v93
	s_nop 1
	global_store_dwordx4 v[4:5], v[154:157], off
	global_store_dwordx4 v[4:5], v[90:93], off offset:256
	s_nop 1
	v_or_b32_e32 v4, 48, v10
	v_mad_i64_i32 v[4:5], s[4:5], v4, s94, v[2:3]
	v_lshl_add_u64 v[4:5], v[4:5], 0, v[6:7]
	v_cvt_pk_f16_f32 v146, v146, v147
	v_cvt_pk_f16_f32 v147, v148, v149
	v_cvt_pk_f16_f32 v148, v130, v131
	v_cvt_pk_f16_f32 v149, v132, v133
	v_cvt_pk_f16_f32 v82, v82, v83
	v_cvt_pk_f16_f32 v83, v84, v85
	v_cvt_pk_f16_f32 v84, v66, v67
	v_cvt_pk_f16_f32 v85, v68, v69
	v_permlane32_swap_b32_e32 v146, v148
	v_permlane32_swap_b32_e32 v147, v149
	v_permlane32_swap_b32_e32 v82, v84
	v_permlane32_swap_b32_e32 v83, v85
	v_permlane16_swap_b32_e32 v146, v148
	v_permlane16_swap_b32_e32 v147, v149
	v_permlane16_swap_b32_e32 v82, v84
	v_permlane16_swap_b32_e32 v83, v85
	s_nop 1
	global_store_dwordx4 v[4:5], v[146:149], off
	global_store_dwordx4 v[4:5], v[82:85], off offset:256
	s_nop 1
	v_add_u32_e32 v4, 0x80, v10
	v_mad_i64_i32 v[4:5], s[4:5], v4, s94, v[2:3]
	v_lshl_add_u64 v[4:5], v[4:5], 0, v[6:7]
	v_cvt_pk_f16_f32 v126, v126, v127
	v_cvt_pk_f16_f32 v127, v128, v129
	v_cvt_pk_f16_f32 v128, v110, v111
	v_cvt_pk_f16_f32 v129, v112, v113
	v_cvt_pk_f16_f32 v62, v62, v63
	v_cvt_pk_f16_f32 v63, v64, v65
	v_cvt_pk_f16_f32 v64, v46, v47
	v_cvt_pk_f16_f32 v65, v48, v49
	v_permlane32_swap_b32_e32 v126, v128
	v_permlane32_swap_b32_e32 v127, v129
	v_permlane32_swap_b32_e32 v62, v64
	v_permlane32_swap_b32_e32 v63, v65
	v_permlane16_swap_b32_e32 v126, v128
	v_permlane16_swap_b32_e32 v127, v129
	v_permlane16_swap_b32_e32 v62, v64
	v_permlane16_swap_b32_e32 v63, v65
	s_nop 1
	global_store_dwordx4 v[4:5], v[126:129], off
	global_store_dwordx4 v[4:5], v[62:65], off offset:256
	s_nop 1
	v_add_u32_e32 v4, 0x90, v10
	v_mad_i64_i32 v[4:5], s[4:5], v4, s94, v[2:3]
	v_lshl_add_u64 v[4:5], v[4:5], 0, v[6:7]
	v_cvt_pk_f16_f32 v118, v118, v119
	v_cvt_pk_f16_f32 v119, v120, v121
	v_cvt_pk_f16_f32 v120, v102, v103
	v_cvt_pk_f16_f32 v121, v104, v105
	v_cvt_pk_f16_f32 v54, v54, v55
	v_cvt_pk_f16_f32 v55, v56, v57
	v_cvt_pk_f16_f32 v56, v38, v39
	v_cvt_pk_f16_f32 v57, v40, v41
	v_permlane32_swap_b32_e32 v118, v120
	v_permlane32_swap_b32_e32 v119, v121
	v_permlane32_swap_b32_e32 v54, v56
	v_permlane32_swap_b32_e32 v55, v57
	v_permlane16_swap_b32_e32 v118, v120
	v_permlane16_swap_b32_e32 v119, v121
	v_permlane16_swap_b32_e32 v54, v56
	v_permlane16_swap_b32_e32 v55, v57
	s_nop 1
	global_store_dwordx4 v[4:5], v[118:121], off
	global_store_dwordx4 v[4:5], v[54:57], off offset:256
	s_nop 1
	v_add_u32_e32 v4, 0xa0, v10
	v_mad_i64_i32 v[4:5], s[4:5], v4, s94, v[2:3]
	v_lshl_add_u64 v[4:5], v[4:5], 0, v[6:7]
	v_cvt_pk_f16_f32 v122, v122, v123
	v_cvt_pk_f16_f32 v123, v124, v125
	v_cvt_pk_f16_f32 v124, v106, v107
	v_cvt_pk_f16_f32 v125, v108, v109
	v_cvt_pk_f16_f32 v58, v58, v59
	v_cvt_pk_f16_f32 v59, v60, v61
	v_cvt_pk_f16_f32 v60, v42, v43
	v_cvt_pk_f16_f32 v61, v44, v45
	v_permlane32_swap_b32_e32 v122, v124
	v_permlane32_swap_b32_e32 v123, v125
	v_permlane32_swap_b32_e32 v58, v60
	v_permlane32_swap_b32_e32 v59, v61
	v_permlane16_swap_b32_e32 v122, v124
	v_permlane16_swap_b32_e32 v123, v125
	v_permlane16_swap_b32_e32 v58, v60
	v_permlane16_swap_b32_e32 v59, v61
	s_nop 1
	global_store_dwordx4 v[4:5], v[122:125], off
	global_store_dwordx4 v[4:5], v[58:61], off offset:256
	s_nop 1
	v_add_u32_e32 v4, 0xb0, v10
	v_mad_i64_i32 v[4:5], s[4:5], v4, s94, v[2:3]
	v_lshl_add_u64 v[4:5], v[4:5], 0, v[6:7]
	v_cvt_pk_f16_f32 v114, v114, v115
	v_cvt_pk_f16_f32 v115, v116, v117
	v_cvt_pk_f16_f32 v116, v98, v99
	v_cvt_pk_f16_f32 v117, v100, v101
	v_cvt_pk_f16_f32 v50, v50, v51
	v_cvt_pk_f16_f32 v51, v52, v53
	v_cvt_pk_f16_f32 v52, v34, v35
	v_cvt_pk_f16_f32 v53, v36, v37
	v_permlane32_swap_b32_e32 v114, v116
	v_permlane32_swap_b32_e32 v115, v117
	v_permlane32_swap_b32_e32 v50, v52
	v_permlane32_swap_b32_e32 v51, v53
	v_permlane16_swap_b32_e32 v114, v116
	v_permlane16_swap_b32_e32 v115, v117
	v_permlane16_swap_b32_e32 v50, v52
	v_permlane16_swap_b32_e32 v51, v53
	s_nop 1
	global_store_dwordx4 v[4:5], v[114:117], off
	global_store_dwordx4 v[4:5], v[50:53], off offset:256
	s_nop 1
	s_mov_b64 s[4:5], 0
